# speedup vs baseline: 1.0571x; 1.0011x over previous
.LBB0_556:
	v_mov_b32_e32 v4, v14
	s_nop 1
	v_permlane32_swap_b32_e32 v14, v4
	v_add_f32_e32 v4, v14, v4
	v_div_scale_f32 v6, s[0:1], v4, v4, 1.0
	v_rcp_f32_e32 v7, v6
	v_mov_b32_e32 v5, v231
	s_nop 1
	v_permlane32_swap_b32_e32 v231, v5
	v_fma_f32 v8, -v6, v7, 1.0
	v_fmac_f32_e32 v7, v8, v7
	v_div_scale_f32 v8, vcc, 1.0, v4, 1.0
	v_mul_f32_e32 v9, v8, v7
	v_fma_f32 v10, -v6, v9, v8
	v_fmac_f32_e32 v9, v10, v7
	v_fma_f32 v6, -v6, v9, v8
	v_div_fmas_f32 v6, v6, v7, v9
	v_div_fixup_f32 v10, v6, v4, 1.0
	v_add_f32_e32 v4, v231, v5
	v_div_scale_f32 v5, s[0:1], v4, v4, s76
	v_rcp_f32_e32 v6, v5
	v_mov_b32_e32 v0, v204
	v_mov_b32_e32 v2, v204
	v_fma_f32 v7, -v5, v6, 1.0
	v_fmac_f32_e32 v6, v7, v6
	v_div_scale_f32 v7, vcc, s76, v4, s76
	v_mul_f32_e32 v8, v7, v6
	v_fma_f32 v9, -v5, v8, v7
	v_fmac_f32_e32 v8, v9, v6
	v_bfe_u32 v0, v0, 5, 1
	v_and_b32_e32 v2, 31, v2
	v_fma_f32 v5, -v5, v8, v7
	v_mul_u32_u24_e32 v2, 0x110, v2
	v_lshlrev_b32_e32 v3, 3, v0
	v_div_fmas_f32 v5, v5, v6, v8
	v_mov_b64_e32 v[6:7], s[86:87]
	v_add3_u32 v13, s79, v2, v3
	flat_load_dwordx2 v[2:3], v[6:7] offset:80
	v_div_fixup_f32 v12, v5, v4, s76
	v_pk_mul_f32 v[14:15], v[146:147], v[12:13] op_sel_hi:[1,0]
	v_lshl_or_b32 v0, v0, 2, s80
	v_pk_fma_f32 v[14:15], v[130:131], v[10:11], v[14:15] op_sel_hi:[1,0,1] neg_lo:[0,0,1] neg_hi:[0,0,1]
	v_pk_mul_f32 v[130:131], v[144:145], v[12:13] op_sel_hi:[1,0]
	v_lshlrev_b64 v[8:9], 2, v[0:1]
	v_pk_fma_f32 v[128:129], v[128:129], v[10:11], v[130:131] op_sel_hi:[1,0,1] neg_lo:[0,0,1] neg_hi:[0,0,1]
	v_pk_mul_f32 v[96:97], v[96:97], v[12:13] op_sel_hi:[1,0]
	v_mul_f32_e32 v0, v129, v129
	v_pk_fma_f32 v[130:131], v[128:129], v[128:129], v[0:1] op_sel_hi:[1,1,0]
	v_mul_f32_e32 v0, v15, v15
	v_pk_fma_f32 v[130:131], v[14:15], v[14:15], v[130:131]
	v_pk_mul_f32 v[98:99], v[98:99], v[12:13] op_sel_hi:[1,0]
	v_pk_add_f32 v[144:145], v[0:1], v[130:131] op_sel_hi:[0,1]
	v_pk_mul_f32 v[130:131], v[150:151], v[12:13] op_sel_hi:[1,0]
	v_pk_fma_f32 v[114:115], v[114:115], v[10:11], v[98:99] op_sel_hi:[1,0,1] neg_lo:[0,0,1] neg_hi:[0,0,1]
	v_pk_fma_f32 v[130:131], v[134:135], v[10:11], v[130:131] op_sel_hi:[1,0,1] neg_lo:[0,0,1] neg_hi:[0,0,1]
	v_pk_mul_f32 v[134:135], v[148:149], v[12:13] op_sel_hi:[1,0]
	v_pk_mul_f32 v[98:99], v[102:103], v[12:13] op_sel_hi:[1,0]
	v_pk_fma_f32 v[132:133], v[132:133], v[10:11], v[134:135] op_sel_hi:[1,0,1] neg_lo:[0,0,1] neg_hi:[0,0,1]
	v_pk_fma_f32 v[102:103], v[118:119], v[10:11], v[98:99] op_sel_hi:[1,0,1] neg_lo:[0,0,1] neg_hi:[0,0,1]
	v_pk_fma_f32 v[134:135], v[132:133], v[132:133], v[144:145]
	v_mul_f32_e32 v0, v133, v133
	v_pk_add_f32 v[134:135], v[0:1], v[134:135] op_sel_hi:[0,1]
	v_pk_fma_f32 v[134:135], v[130:131], v[130:131], v[134:135]
	v_mul_f32_e32 v0, v131, v131
	v_pk_add_f32 v[144:145], v[0:1], v[134:135] op_sel_hi:[0,1]
	v_pk_mul_f32 v[134:135], v[154:155], v[12:13] op_sel_hi:[1,0]
	v_pk_mul_f32 v[98:99], v[100:101], v[12:13] op_sel_hi:[1,0]
	v_pk_fma_f32 v[134:135], v[138:139], v[10:11], v[134:135] op_sel_hi:[1,0,1] neg_lo:[0,0,1] neg_hi:[0,0,1]
	v_pk_mul_f32 v[138:139], v[152:153], v[12:13] op_sel_hi:[1,0]
	v_pk_mul_f32 v[100:101], v[104:105], v[12:13] op_sel_hi:[1,0]
	v_pk_fma_f32 v[136:137], v[136:137], v[10:11], v[138:139] op_sel_hi:[1,0,1] neg_lo:[0,0,1] neg_hi:[0,0,1]
	v_pk_mul_f32 v[104:105], v[108:109], v[12:13] op_sel_hi:[1,0]
	v_pk_fma_f32 v[138:139], v[136:137], v[136:137], v[144:145]
	v_mul_f32_e32 v0, v137, v137
	v_pk_add_f32 v[138:139], v[0:1], v[138:139] op_sel_hi:[0,1]
	v_pk_fma_f32 v[138:139], v[134:135], v[134:135], v[138:139]
	v_mul_f32_e32 v0, v135, v135
	v_pk_add_f32 v[144:145], v[0:1], v[138:139] op_sel_hi:[0,1]
	v_pk_mul_f32 v[138:139], v[158:159], v[12:13] op_sel_hi:[1,0]
	v_pk_fma_f32 v[104:105], v[124:125], v[10:11], v[104:105] op_sel_hi:[1,0,1] neg_lo:[0,0,1] neg_hi:[0,0,1]
	v_pk_fma_f32 v[138:139], v[142:143], v[10:11], v[138:139] op_sel_hi:[1,0,1] neg_lo:[0,0,1] neg_hi:[0,0,1]
	v_pk_mul_f32 v[142:143], v[156:157], v[12:13] op_sel_hi:[1,0]
	v_pk_mul_f32 v[64:65], v[64:65], v[12:13] op_sel_hi:[1,0]
	v_pk_fma_f32 v[140:141], v[140:141], v[10:11], v[142:143] op_sel_hi:[1,0,1] neg_lo:[0,0,1] neg_hi:[0,0,1]
	v_pk_mul_f32 v[66:67], v[66:67], v[12:13] op_sel_hi:[1,0]
	v_pk_fma_f32 v[142:143], v[140:141], v[140:141], v[144:145]
	v_mul_f32_e32 v0, v141, v141
	v_pk_add_f32 v[142:143], v[0:1], v[142:143] op_sel_hi:[0,1]
	v_pk_fma_f32 v[142:143], v[138:139], v[138:139], v[142:143]
	v_mul_f32_e32 v0, v139, v139
	v_pk_add_f32 v[144:145], v[0:1], v[142:143] op_sel_hi:[0,1]
	v_pk_fma_f32 v[142:143], v[112:113], v[10:11], v[96:97] op_sel_hi:[1,0,1] neg_lo:[0,0,1] neg_hi:[0,0,1]
	v_pk_fma_f32 v[112:113], v[116:117], v[10:11], v[98:99] op_sel_hi:[1,0,1] neg_lo:[0,0,1] neg_hi:[0,0,1]
	v_pk_fma_f32 v[96:97], v[142:143], v[142:143], v[144:145]
	v_mul_f32_e32 v0, v143, v143
	v_pk_add_f32 v[96:97], v[0:1], v[96:97] op_sel_hi:[0,1]
	v_pk_fma_f32 v[96:97], v[114:115], v[114:115], v[96:97]
	v_mul_f32_e32 v0, v115, v115
	v_pk_add_f32 v[96:97], v[0:1], v[96:97] op_sel_hi:[0,1]
	v_pk_fma_f32 v[96:97], v[112:113], v[112:113], v[96:97]
	v_mul_f32_e32 v0, v113, v113
	v_pk_add_f32 v[96:97], v[0:1], v[96:97] op_sel_hi:[0,1]
	v_pk_fma_f32 v[96:97], v[102:103], v[102:103], v[96:97]
	v_mul_f32_e32 v0, v103, v103
	v_pk_add_f32 v[96:97], v[0:1], v[96:97] op_sel_hi:[0,1]
	v_pk_mul_f32 v[98:99], v[106:107], v[12:13] op_sel_hi:[1,0]
	v_pk_fma_f32 v[106:107], v[120:121], v[10:11], v[100:101] op_sel_hi:[1,0,1] neg_lo:[0,0,1] neg_hi:[0,0,1]
	v_pk_fma_f32 v[98:99], v[122:123], v[10:11], v[98:99] op_sel_hi:[1,0,1] neg_lo:[0,0,1] neg_hi:[0,0,1]
	v_pk_fma_f32 v[96:97], v[106:107], v[106:107], v[96:97]
	v_mul_f32_e32 v0, v107, v107
	v_pk_add_f32 v[96:97], v[0:1], v[96:97] op_sel_hi:[0,1]
	v_pk_fma_f32 v[96:97], v[98:99], v[98:99], v[96:97]
	v_mul_f32_e32 v0, v99, v99
	v_pk_add_f32 v[100:101], v[0:1], v[96:97] op_sel_hi:[0,1]
	v_pk_mul_f32 v[96:97], v[110:111], v[12:13] op_sel_hi:[1,0]
	v_pk_fma_f32 v[100:101], v[104:105], v[104:105], v[100:101]
	v_mul_f32_e32 v0, v105, v105
	s_waitcnt vmcnt(0) lgkmcnt(0)
	v_lshl_add_u64 v[2:3], v[2:3], 0, v[8:9]
	flat_load_dwordx4 v[2:5], v[2:3]
	v_pk_fma_f32 v[96:97], v[126:127], v[10:11], v[96:97] op_sel_hi:[1,0,1] neg_lo:[0,0,1] neg_hi:[0,0,1]
	v_pk_add_f32 v[100:101], v[0:1], v[100:101] op_sel_hi:[0,1]
	v_pk_fma_f32 v[100:101], v[96:97], v[96:97], v[100:101]
	v_mul_f32_e32 v0, v97, v97
	v_pk_add_f32 v[108:109], v[0:1], v[100:101] op_sel_hi:[0,1]
	v_pk_fma_f32 v[100:101], v[80:81], v[10:11], v[64:65] op_sel_hi:[1,0,1] neg_lo:[0,0,1] neg_hi:[0,0,1]
	v_pk_fma_f32 v[82:83], v[82:83], v[10:11], v[66:67] op_sel_hi:[1,0,1] neg_lo:[0,0,1] neg_hi:[0,0,1]
	v_pk_fma_f32 v[64:65], v[100:101], v[100:101], v[108:109]
	v_mul_f32_e32 v0, v101, v101
	v_pk_add_f32 v[64:65], v[0:1], v[64:65] op_sel_hi:[0,1]
	v_pk_mul_f32 v[66:67], v[70:71], v[12:13] op_sel_hi:[1,0]
	v_pk_fma_f32 v[64:65], v[82:83], v[82:83], v[64:65]
	v_mul_f32_e32 v0, v83, v83
	v_pk_fma_f32 v[70:71], v[86:87], v[10:11], v[66:67] op_sel_hi:[1,0,1] neg_lo:[0,0,1] neg_hi:[0,0,1]
	v_pk_mul_f32 v[66:67], v[68:69], v[12:13] op_sel_hi:[1,0]
	v_pk_add_f32 v[64:65], v[0:1], v[64:65] op_sel_hi:[0,1]
	v_pk_fma_f32 v[80:81], v[84:85], v[10:11], v[66:67] op_sel_hi:[1,0,1] neg_lo:[0,0,1] neg_hi:[0,0,1]
	v_pk_mul_f32 v[68:69], v[72:73], v[12:13] op_sel_hi:[1,0]
	v_pk_fma_f32 v[64:65], v[80:81], v[80:81], v[64:65]
	v_mul_f32_e32 v0, v81, v81
	v_pk_add_f32 v[64:65], v[0:1], v[64:65] op_sel_hi:[0,1]
	v_pk_fma_f32 v[64:65], v[70:71], v[70:71], v[64:65]
	v_mul_f32_e32 v0, v71, v71
	v_pk_add_f32 v[64:65], v[0:1], v[64:65] op_sel_hi:[0,1]
	v_pk_mul_f32 v[66:67], v[74:75], v[12:13] op_sel_hi:[1,0]
	v_pk_fma_f32 v[74:75], v[88:89], v[10:11], v[68:69] op_sel_hi:[1,0,1] neg_lo:[0,0,1] neg_hi:[0,0,1]
	v_pk_fma_f32 v[66:67], v[90:91], v[10:11], v[66:67] op_sel_hi:[1,0,1] neg_lo:[0,0,1] neg_hi:[0,0,1]
	v_pk_fma_f32 v[64:65], v[74:75], v[74:75], v[64:65]
	v_mul_f32_e32 v0, v75, v75
	v_pk_add_f32 v[64:65], v[0:1], v[64:65] op_sel_hi:[0,1]
	v_pk_fma_f32 v[64:65], v[66:67], v[66:67], v[64:65]
	v_mul_f32_e32 v0, v67, v67
	v_pk_mul_f32 v[72:73], v[76:77], v[12:13] op_sel_hi:[1,0]
	v_pk_add_f32 v[68:69], v[0:1], v[64:65] op_sel_hi:[0,1]
	v_pk_fma_f32 v[72:73], v[92:93], v[10:11], v[72:73] op_sel_hi:[1,0,1] neg_lo:[0,0,1] neg_hi:[0,0,1]
	v_pk_mul_f32 v[64:65], v[78:79], v[12:13] op_sel_hi:[1,0]
	v_pk_fma_f32 v[68:69], v[72:73], v[72:73], v[68:69]
	v_mul_f32_e32 v0, v73, v73
	v_pk_fma_f32 v[64:65], v[94:95], v[10:11], v[64:65] op_sel_hi:[1,0,1] neg_lo:[0,0,1] neg_hi:[0,0,1]
	v_pk_add_f32 v[68:69], v[0:1], v[68:69] op_sel_hi:[0,1]
	v_pk_fma_f32 v[68:69], v[64:65], v[64:65], v[68:69]
	v_mul_f32_e32 v0, v65, v65
	v_pk_mul_f32 v[32:33], v[32:33], v[12:13] op_sel_hi:[1,0]
	v_pk_add_f32 v[76:77], v[0:1], v[68:69] op_sel_hi:[0,1]
	v_pk_fma_f32 v[68:69], v[48:49], v[10:11], v[32:33] op_sel_hi:[1,0,1] neg_lo:[0,0,1] neg_hi:[0,0,1]
	v_pk_mul_f32 v[34:35], v[34:35], v[12:13] op_sel_hi:[1,0]
	v_pk_fma_f32 v[32:33], v[68:69], v[68:69], v[76:77]
	v_mul_f32_e32 v0, v69, v69
	v_pk_fma_f32 v[50:51], v[50:51], v[10:11], v[34:35] op_sel_hi:[1,0,1] neg_lo:[0,0,1] neg_hi:[0,0,1]
	v_pk_add_f32 v[32:33], v[0:1], v[32:33] op_sel_hi:[0,1]
	v_pk_fma_f32 v[32:33], v[50:51], v[50:51], v[32:33]
	v_mul_f32_e32 v0, v51, v51
	v_pk_mul_f32 v[36:37], v[36:37], v[12:13] op_sel_hi:[1,0]
	v_pk_add_f32 v[32:33], v[0:1], v[32:33] op_sel_hi:[0,1]
	v_pk_fma_f32 v[48:49], v[52:53], v[10:11], v[36:37] op_sel_hi:[1,0,1] neg_lo:[0,0,1] neg_hi:[0,0,1]
	v_pk_mul_f32 v[34:35], v[38:39], v[12:13] op_sel_hi:[1,0]
	v_pk_fma_f32 v[32:33], v[48:49], v[48:49], v[32:33]
	v_mul_f32_e32 v0, v49, v49
	v_pk_fma_f32 v[34:35], v[54:55], v[10:11], v[34:35] op_sel_hi:[1,0,1] neg_lo:[0,0,1] neg_hi:[0,0,1]
	v_pk_add_f32 v[32:33], v[0:1], v[32:33] op_sel_hi:[0,1]
	v_pk_fma_f32 v[32:33], v[34:35], v[34:35], v[32:33]
	v_mul_f32_e32 v0, v35, v35
	v_pk_mul_f32 v[38:39], v[40:41], v[12:13] op_sel_hi:[1,0]
	v_pk_add_f32 v[36:37], v[0:1], v[32:33] op_sel_hi:[0,1]
	v_pk_fma_f32 v[38:39], v[56:57], v[10:11], v[38:39] op_sel_hi:[1,0,1] neg_lo:[0,0,1] neg_hi:[0,0,1]
	v_pk_mul_f32 v[32:33], v[42:43], v[12:13] op_sel_hi:[1,0]
	v_pk_fma_f32 v[36:37], v[38:39], v[38:39], v[36:37]
	v_mul_f32_e32 v0, v39, v39
	v_pk_fma_f32 v[32:33], v[58:59], v[10:11], v[32:33] op_sel_hi:[1,0,1] neg_lo:[0,0,1] neg_hi:[0,0,1]
	v_pk_add_f32 v[36:37], v[0:1], v[36:37] op_sel_hi:[0,1]
	v_pk_fma_f32 v[36:37], v[32:33], v[32:33], v[36:37]
	v_mul_f32_e32 v0, v33, v33
	v_pk_add_f32 v[40:41], v[0:1], v[36:37] op_sel_hi:[0,1]
	v_pk_mul_f32 v[36:37], v[46:47], v[12:13] op_sel_hi:[1,0]
	v_pk_mul_f32 v[42:43], v[44:45], v[12:13] op_sel_hi:[1,0]
	v_pk_fma_f32 v[36:37], v[62:63], v[10:11], v[36:37] op_sel_hi:[1,0,1] neg_lo:[0,0,1] neg_hi:[0,0,1]
	v_pk_fma_f32 v[10:11], v[60:61], v[10:11], v[42:43] op_sel_hi:[1,0,1] neg_lo:[0,0,1] neg_hi:[0,0,1]
	s_cmp_lt_i32 s45, 0
	v_pk_fma_f32 v[40:41], v[10:11], v[10:11], v[40:41]
	v_mul_f32_e32 v0, v11, v11
	v_pk_add_f32 v[40:41], v[0:1], v[40:41] op_sel_hi:[0,1]
	v_pk_fma_f32 v[40:41], v[36:37], v[36:37], v[40:41]
	v_mul_f32_e32 v0, v37, v37
	v_pk_add_f32 v[40:41], v[0:1], v[40:41] op_sel_hi:[0,1]
	v_mov_b32_e32 v0, v40
	s_nop 1
	v_permlane32_swap_b32_e32 v40, v0
	v_add_f32_e32 v0, v40, v0
	v_fmamk_f32 v0, v0, 0x3c000000, v253
	v_cmp_gt_f32_e32 vcc, s33, v0
	v_mul_f32_e32 v12, 0x4b800000, v0
	s_nop 0
	v_cndmask_b32_e32 v0, v0, v12, vcc
	v_rsq_f32_e32 v0, v0
	s_nop 0
	v_mul_f32_e32 v12, 0x45800000, v0
	v_cndmask_b32_e32 v0, v0, v12, vcc
	v_mul_f32_e32 v0, v225, v0
	v_pk_mul_f32 v[40:41], v[128:129], v[0:1] op_sel_hi:[1,0]
	v_pk_mul_f32 v[14:15], v[14:15], v[0:1] op_sel_hi:[1,0]
	s_waitcnt vmcnt(0) lgkmcnt(0)
	v_pk_mul_f32 v[2:3], v[2:3], v[40:41]
	v_pk_mul_f32 v[4:5], v[4:5], v[14:15]
	v_cvt_pk_bf16_f32 v2, v2, v3
	v_cvt_pk_bf16_f32 v3, v4, v5
	ds_write_b64 v13, v[2:3]
	flat_load_dwordx2 v[2:3], v[6:7] offset:80
	v_pk_mul_f32 v[14:15], v[132:133], v[0:1] op_sel_hi:[1,0]
	s_waitcnt vmcnt(0) lgkmcnt(0)
	v_lshl_add_u64 v[2:3], v[2:3], 0, v[8:9]
	flat_load_dwordx4 v[2:5], v[2:3] offset:32
	s_waitcnt vmcnt(0) lgkmcnt(0)
	v_pk_mul_f32 v[2:3], v[2:3], v[14:15]
	v_pk_mul_f32 v[14:15], v[130:131], v[0:1] op_sel_hi:[1,0]
	v_cvt_pk_bf16_f32 v2, v2, v3
	v_pk_mul_f32 v[4:5], v[4:5], v[14:15]
	v_pk_mul_f32 v[14:15], v[136:137], v[0:1] op_sel_hi:[1,0]
	v_cvt_pk_bf16_f32 v3, v4, v5
	ds_write_b64 v13, v[2:3] offset:16
	flat_load_dwordx2 v[2:3], v[6:7] offset:80
	s_waitcnt vmcnt(0) lgkmcnt(0)
	v_lshl_add_u64 v[2:3], v[2:3], 0, v[8:9]
	flat_load_dwordx4 v[2:5], v[2:3] offset:64
	s_waitcnt vmcnt(0) lgkmcnt(0)
	v_pk_mul_f32 v[2:3], v[2:3], v[14:15]
	v_pk_mul_f32 v[14:15], v[134:135], v[0:1] op_sel_hi:[1,0]
	v_cvt_pk_bf16_f32 v2, v2, v3
	v_pk_mul_f32 v[4:5], v[4:5], v[14:15]
	v_pk_mul_f32 v[14:15], v[140:141], v[0:1] op_sel_hi:[1,0]
	v_cvt_pk_bf16_f32 v3, v4, v5
	ds_write_b64 v13, v[2:3] offset:32
	flat_load_dwordx2 v[2:3], v[6:7] offset:80
	s_waitcnt vmcnt(0) lgkmcnt(0)
	v_lshl_add_u64 v[2:3], v[2:3], 0, v[8:9]
	flat_load_dwordx4 v[2:5], v[2:3] offset:96
	s_waitcnt vmcnt(0) lgkmcnt(0)
	v_pk_mul_f32 v[2:3], v[2:3], v[14:15]
	v_pk_mul_f32 v[14:15], v[138:139], v[0:1] op_sel_hi:[1,0]
	v_cvt_pk_bf16_f32 v2, v2, v3
	v_pk_mul_f32 v[4:5], v[4:5], v[14:15]
	v_pk_mul_f32 v[14:15], v[142:143], v[0:1] op_sel_hi:[1,0]
	v_cvt_pk_bf16_f32 v3, v4, v5
	ds_write_b64 v13, v[2:3] offset:48
	flat_load_dwordx2 v[2:3], v[6:7] offset:80
	s_waitcnt vmcnt(0) lgkmcnt(0)
	v_lshl_add_u64 v[2:3], v[2:3], 0, v[8:9]
	flat_load_dwordx4 v[2:5], v[2:3] offset:128
	s_waitcnt vmcnt(0) lgkmcnt(0)
	v_pk_mul_f32 v[2:3], v[14:15], v[2:3]
	v_pk_mul_f32 v[14:15], v[114:115], v[0:1] op_sel_hi:[1,0]
	v_cvt_pk_bf16_f32 v2, v2, v3
	v_pk_mul_f32 v[4:5], v[14:15], v[4:5]
	v_pk_mul_f32 v[14:15], v[112:113], v[0:1] op_sel_hi:[1,0]
	v_cvt_pk_bf16_f32 v3, v4, v5
	ds_write_b64 v13, v[2:3] offset:64
	flat_load_dwordx2 v[2:3], v[6:7] offset:80
	s_waitcnt vmcnt(0) lgkmcnt(0)
	v_lshl_add_u64 v[2:3], v[2:3], 0, v[8:9]
	flat_load_dwordx4 v[2:5], v[2:3] offset:160
	s_waitcnt vmcnt(0) lgkmcnt(0)
	v_pk_mul_f32 v[2:3], v[14:15], v[2:3]
	v_pk_mul_f32 v[14:15], v[102:103], v[0:1] op_sel_hi:[1,0]
	v_cvt_pk_bf16_f32 v2, v2, v3
	v_pk_mul_f32 v[4:5], v[14:15], v[4:5]
	v_pk_mul_f32 v[14:15], v[106:107], v[0:1] op_sel_hi:[1,0]
	v_cvt_pk_bf16_f32 v3, v4, v5
	ds_write_b64 v13, v[2:3] offset:80
	flat_load_dwordx2 v[2:3], v[6:7] offset:80
	s_waitcnt vmcnt(0) lgkmcnt(0)
	v_lshl_add_u64 v[2:3], v[2:3], 0, v[8:9]
	flat_load_dwordx4 v[2:5], v[2:3] offset:192
	s_waitcnt vmcnt(0) lgkmcnt(0)
	v_pk_mul_f32 v[2:3], v[14:15], v[2:3]
	v_pk_mul_f32 v[14:15], v[98:99], v[0:1] op_sel_hi:[1,0]
	v_cvt_pk_bf16_f32 v2, v2, v3
	v_pk_mul_f32 v[4:5], v[14:15], v[4:5]
	v_pk_mul_f32 v[14:15], v[104:105], v[0:1] op_sel_hi:[1,0]
	v_cvt_pk_bf16_f32 v3, v4, v5
	ds_write_b64 v13, v[2:3] offset:96
	flat_load_dwordx2 v[2:3], v[6:7] offset:80
	s_waitcnt vmcnt(0) lgkmcnt(0)
	v_lshl_add_u64 v[2:3], v[2:3], 0, v[8:9]
	flat_load_dwordx4 v[2:5], v[2:3] offset:224
	s_waitcnt vmcnt(0) lgkmcnt(0)
	v_pk_mul_f32 v[2:3], v[14:15], v[2:3]
	v_pk_mul_f32 v[14:15], v[96:97], v[0:1] op_sel_hi:[1,0]
	v_cvt_pk_bf16_f32 v2, v2, v3
	v_pk_mul_f32 v[4:5], v[14:15], v[4:5]
	v_pk_mul_f32 v[14:15], v[100:101], v[0:1] op_sel_hi:[1,0]
	v_cvt_pk_bf16_f32 v3, v4, v5
	ds_write_b64 v13, v[2:3] offset:112
	flat_load_dwordx2 v[2:3], v[6:7] offset:80
	s_waitcnt vmcnt(0) lgkmcnt(0)
	v_lshl_add_u64 v[2:3], v[2:3], 0, v[8:9]
	flat_load_dwordx4 v[2:5], v[2:3] offset:256
	s_waitcnt vmcnt(0) lgkmcnt(0)
	v_pk_mul_f32 v[2:3], v[14:15], v[2:3]
	v_pk_mul_f32 v[14:15], v[82:83], v[0:1] op_sel_hi:[1,0]
	v_cvt_pk_bf16_f32 v2, v2, v3
	v_pk_mul_f32 v[4:5], v[14:15], v[4:5]
	v_pk_mul_f32 v[14:15], v[80:81], v[0:1] op_sel_hi:[1,0]
	v_cvt_pk_bf16_f32 v3, v4, v5
	ds_write_b64 v13, v[2:3] offset:128
	flat_load_dwordx2 v[2:3], v[6:7] offset:80
	s_waitcnt vmcnt(0) lgkmcnt(0)
	v_lshl_add_u64 v[2:3], v[2:3], 0, v[8:9]
	flat_load_dwordx4 v[2:5], v[2:3] offset:288
	s_waitcnt vmcnt(0) lgkmcnt(0)
	v_pk_mul_f32 v[2:3], v[14:15], v[2:3]
	v_pk_mul_f32 v[14:15], v[70:71], v[0:1] op_sel_hi:[1,0]
	v_cvt_pk_bf16_f32 v2, v2, v3
	v_pk_mul_f32 v[4:5], v[14:15], v[4:5]
	v_pk_mul_f32 v[14:15], v[74:75], v[0:1] op_sel_hi:[1,0]
	v_cvt_pk_bf16_f32 v3, v4, v5
	ds_write_b64 v13, v[2:3] offset:144
	flat_load_dwordx2 v[2:3], v[6:7] offset:80
	s_waitcnt vmcnt(0) lgkmcnt(0)
	v_lshl_add_u64 v[2:3], v[2:3], 0, v[8:9]
	flat_load_dwordx4 v[2:5], v[2:3] offset:320
	s_waitcnt vmcnt(0) lgkmcnt(0)
	v_pk_mul_f32 v[2:3], v[14:15], v[2:3]
	v_pk_mul_f32 v[14:15], v[66:67], v[0:1] op_sel_hi:[1,0]
	v_cvt_pk_bf16_f32 v2, v2, v3
	v_pk_mul_f32 v[4:5], v[14:15], v[4:5]
	v_pk_mul_f32 v[14:15], v[72:73], v[0:1] op_sel_hi:[1,0]
	v_cvt_pk_bf16_f32 v3, v4, v5
	ds_write_b64 v13, v[2:3] offset:160
	flat_load_dwordx2 v[2:3], v[6:7] offset:80
	s_waitcnt vmcnt(0) lgkmcnt(0)
	v_lshl_add_u64 v[2:3], v[2:3], 0, v[8:9]
	flat_load_dwordx4 v[2:5], v[2:3] offset:352
	s_waitcnt vmcnt(0) lgkmcnt(0)
	v_pk_mul_f32 v[2:3], v[14:15], v[2:3]
	v_pk_mul_f32 v[14:15], v[64:65], v[0:1] op_sel_hi:[1,0]
	v_cvt_pk_bf16_f32 v2, v2, v3
	v_pk_mul_f32 v[4:5], v[14:15], v[4:5]
	v_pk_mul_f32 v[14:15], v[68:69], v[0:1] op_sel_hi:[1,0]
	v_cvt_pk_bf16_f32 v3, v4, v5
	ds_write_b64 v13, v[2:3] offset:176
	flat_load_dwordx2 v[2:3], v[6:7] offset:80
	s_waitcnt vmcnt(0) lgkmcnt(0)
	v_lshl_add_u64 v[2:3], v[2:3], 0, v[8:9]
	flat_load_dwordx4 v[2:5], v[2:3] offset:384
	s_waitcnt vmcnt(0) lgkmcnt(0)
	v_pk_mul_f32 v[2:3], v[14:15], v[2:3]
	v_pk_mul_f32 v[14:15], v[50:51], v[0:1] op_sel_hi:[1,0]
	v_cvt_pk_bf16_f32 v2, v2, v3
	v_pk_mul_f32 v[4:5], v[14:15], v[4:5]
	v_pk_mul_f32 v[14:15], v[48:49], v[0:1] op_sel_hi:[1,0]
	v_cvt_pk_bf16_f32 v3, v4, v5
	ds_write_b64 v13, v[2:3] offset:192
	flat_load_dwordx2 v[2:3], v[6:7] offset:80
	s_waitcnt vmcnt(0) lgkmcnt(0)
	v_lshl_add_u64 v[2:3], v[2:3], 0, v[8:9]
	flat_load_dwordx4 v[2:5], v[2:3] offset:416
	s_waitcnt vmcnt(0) lgkmcnt(0)
	v_pk_mul_f32 v[2:3], v[14:15], v[2:3]
	v_pk_mul_f32 v[14:15], v[34:35], v[0:1] op_sel_hi:[1,0]
	v_cvt_pk_bf16_f32 v2, v2, v3
	v_pk_mul_f32 v[4:5], v[14:15], v[4:5]
	v_pk_mul_f32 v[14:15], v[38:39], v[0:1] op_sel_hi:[1,0]
	v_cvt_pk_bf16_f32 v3, v4, v5
	ds_write_b64 v13, v[2:3] offset:208
	flat_load_dwordx2 v[2:3], v[6:7] offset:80
	s_waitcnt vmcnt(0) lgkmcnt(0)
	v_lshl_add_u64 v[2:3], v[2:3], 0, v[8:9]
	flat_load_dwordx4 v[2:5], v[2:3] offset:448
	s_waitcnt vmcnt(0) lgkmcnt(0)
	v_pk_mul_f32 v[2:3], v[14:15], v[2:3]
	v_pk_mul_f32 v[14:15], v[32:33], v[0:1] op_sel_hi:[1,0]
	v_cvt_pk_bf16_f32 v2, v2, v3
	v_pk_mul_f32 v[4:5], v[14:15], v[4:5]
	s_nop 0
	v_cvt_pk_bf16_f32 v3, v4, v5
	ds_write_b64 v13, v[2:3] offset:224
	flat_load_dwordx2 v[2:3], v[6:7] offset:80
	v_pk_mul_f32 v[6:7], v[10:11], v[0:1] op_sel_hi:[1,0]
	s_waitcnt vmcnt(0) lgkmcnt(0)
	v_lshl_add_u64 v[2:3], v[2:3], 0, v[8:9]
	flat_load_dwordx4 v[2:5], v[2:3] offset:480
	s_waitcnt vmcnt(0) lgkmcnt(0)
	v_pk_mul_f32 v[2:3], v[6:7], v[2:3]
	v_pk_mul_f32 v[6:7], v[36:37], v[0:1] op_sel_hi:[1,0]
	v_cvt_pk_bf16_f32 v2, v2, v3
	v_pk_mul_f32 v[4:5], v[6:7], v[4:5]
	v_mov_b32_e32 v0, v204
	v_cvt_pk_bf16_f32 v3, v4, v5
	ds_write_b64 v13, v[2:3] offset:240
	s_nop 0
	v_and_b32_e32 v2, 15, v0
	v_lshl_add_u32 v3, v2, 4, s79
	v_lshlrev_b32_e32 v2, 3, v2
	v_bfe_u32 v4, v0, 4, 2
	s_cbranch_scc1 .LBB0_558
	v_mad_u32_u24 v5, v4, s74, v3
	ds_read_b128 v[6:9], v5
	s_add_i32 s0, s45, s89
	v_or_b32_e32 v0, s0, v4
	v_lshl_or_b32 v0, v0, 11, v2
	v_lshl_add_u64 v[10:11], v[0:1], 1, v[214:215]
	s_waitcnt lgkmcnt(0)
	flat_store_dwordx4 v[10:11], v[6:9] nt
	ds_read_b128 v[6:9], v5 offset:1088
	v_or_b32_e32 v10, 0x2000, v0
	v_mov_b32_e32 v11, v1
	v_lshl_add_u64 v[10:11], v[10:11], 1, v[214:215]
	s_waitcnt lgkmcnt(0)
	flat_store_dwordx4 v[10:11], v[6:9] nt
	ds_read_b128 v[6:9], v5 offset:2176
	v_or_b32_e32 v10, 0x4000, v0
	v_mov_b32_e32 v11, v1
	v_lshl_add_u64 v[10:11], v[10:11], 1, v[214:215]
	v_or_b32_e32 v0, 0x6000, v0
	s_waitcnt lgkmcnt(0)
	flat_store_dwordx4 v[10:11], v[6:9] nt
	ds_read_b128 v[6:9], v5 offset:3264
	v_lshl_add_u64 v[10:11], v[0:1], 1, v[214:215]
	s_waitcnt lgkmcnt(0)
	flat_store_dwordx4 v[10:11], v[6:9] nt
.LBB0_558:
	v_or_b32_e32 v5, 16, v4
	v_add_u32_e32 v0, s45, v5
	v_cmp_lt_i32_e32 vcc, -1, v0
	s_and_saveexec_b64 s[6:7], vcc
	s_cbranch_execz .LBB0_560
	v_mad_u32_u24 v5, v5, s74, v3
	ds_read_b128 v[6:9], v5
	v_mov_b32_e32 v5, s89
	v_cmp_lt_u32_e32 vcc, 15, v0
	s_nop 1
	v_cndmask_b32_e32 v5, v212, v5, vcc
	v_add_u32_e32 v0, v5, v0
	v_lshl_or_b32 v0, v0, 11, v2
	v_lshl_add_u64 v[10:11], v[0:1], 1, v[214:215]
	s_waitcnt lgkmcnt(0)
	flat_store_dwordx4 v[10:11], v[6:9] nt
.LBB0_560:
	s_or_b64 exec, exec, s[6:7]
	v_or_b32_e32 v5, 20, v4
	v_add_u32_e32 v0, s45, v5
	v_cmp_lt_i32_e32 vcc, -1, v0
	s_and_saveexec_b64 s[6:7], vcc
	s_cbranch_execz .LBB0_562
	v_mad_u32_u24 v5, v5, s74, v3
	ds_read_b128 v[6:9], v5
	v_mov_b32_e32 v5, s89
	v_cmp_lt_u32_e32 vcc, 15, v0
	s_nop 1
	v_cndmask_b32_e32 v5, v212, v5, vcc
	v_add_u32_e32 v0, v5, v0
	v_lshl_or_b32 v0, v0, 11, v2
	v_lshl_add_u64 v[10:11], v[0:1], 1, v[214:215]
	s_waitcnt lgkmcnt(0)
	flat_store_dwordx4 v[10:11], v[6:9] nt
.LBB0_562:
	s_or_b64 exec, exec, s[6:7]
	v_or_b32_e32 v5, 24, v4
	v_add_u32_e32 v0, s45, v5
	v_cmp_lt_i32_e32 vcc, -1, v0
	s_and_saveexec_b64 s[6:7], vcc
	s_cbranch_execz .LBB0_564
	v_mad_u32_u24 v5, v5, s74, v3
	ds_read_b128 v[6:9], v5
	v_mov_b32_e32 v5, s89
	v_cmp_lt_u32_e32 vcc, 15, v0
	s_nop 1
	v_cndmask_b32_e32 v5, v212, v5, vcc
	v_add_u32_e32 v0, v5, v0
	v_lshl_or_b32 v0, v0, 11, v2
	v_lshl_add_u64 v[10:11], v[0:1], 1, v[214:215]
	s_waitcnt lgkmcnt(0)
	flat_store_dwordx4 v[10:11], v[6:9] nt
.LBB0_564:
	s_or_b64 exec, exec, s[6:7]
	v_or_b32_e32 v4, 28, v4
	v_add_u32_e32 v0, s45, v4
	v_cmp_lt_i32_e32 vcc, -1, v0
	s_and_saveexec_b64 s[6:7], vcc
	s_cbranch_execz .LBB0_418
	v_mad_u32_u24 v3, v4, s74, v3
	ds_read_b128 v[4:7], v3
	v_mov_b32_e32 v3, s89
	v_cmp_lt_u32_e32 vcc, 15, v0
	s_nop 1
	v_cndmask_b32_e32 v3, v212, v3, vcc
	v_add_u32_e32 v0, v3, v0
	v_lshl_or_b32 v0, v0, 11, v2
	v_lshl_add_u64 v[2:3], v[0:1], 1, v[214:215]
	s_waitcnt lgkmcnt(0)
	flat_store_dwordx4 v[2:3], v[4:7] nt
	s_branch .LBB0_418
